# rotary/final-norm/hnorm loops rescheduled by hand: loads issued up front, loop-invariant weights hoisted
# speedup vs baseline: 1.1551x; 1.0210x over previous
.LBB0_18:
	s_ashr_i32 s5, s26, 6
	s_lshl_b32 s4, s58, 3
	v_writelane_b32 v255, s5, 15
	s_add_i32 s4, s5, s4
	v_writelane_b32 v255, s4, 16
	v_and_b32_e32 v198, 63, v197
	s_andn2_b64 vcc, exec, s[2:3]
	v_writelane_b32 v255, s5, 17
	v_writelane_b32 v255, s20, 18
	s_lshl_b32 s46, s59, 3
	s_nop 0
	v_writelane_b32 v255, s21, 19
	s_cbranch_vccnz .LBB0_461
	v_readlane_b32 s0, v255, 14
	s_cmp_lt_i32 s0, 8
	s_mov_b64 s[0:1], -1
	s_cbranch_scc1 .LBB0_114
	v_readlane_b32 s0, v255, 14
	s_cmp_lt_i32 s0, 11
	s_mov_b64 s[0:1], -1
	s_cbranch_scc1 .LBB0_97
	v_readlane_b32 s0, v255, 14
	s_cmp_lt_i32 s0, 12
	s_mov_b64 s[0:1], -1
	s_cbranch_scc1 .LBB0_34
	v_readlane_b32 s0, v255, 14
	s_cmp_lt_i32 s0, 14
	s_mov_b64 s[0:1], -1
	s_cbranch_scc1 .LBB0_28
	v_readlane_b32 s0, v255, 14
	s_cmp_eq_u32 s0, 14
	s_cbranch_scc0 .LBB0_27
	v_readlane_b32 s0, v255, 16
	s_cmpk_gt_i32 s0, 0x407f
	v_readlane_b32 s1, v255, 17
	s_cbranch_scc1 .LBB0_27
	v_xor_b32_e32 v0, 16, v225
	v_cmp_lt_i32_e32 vcc, v0, v227
	s_load_dwordx4 s[0:3], s[20:21], 0xe0
	v_mov_b32_e32 v3, v1
	v_cndmask_b32_e32 v0, v225, v0, vcc
	s_waitcnt vmcnt(0)
	v_lshlrev_b32_e32 v28, 2, v0
	v_xor_b32_e32 v0, 32, v225
	v_cmp_lt_i32_e32 vcc, v0, v227
	s_nop 1
	v_cndmask_b32_e32 v0, v225, v0, vcc
	v_lshlrev_b32_e32 v29, 2, v0
	v_lshlrev_b32_e32 v0, 4, v198
	v_or_b32_e32 v2, 0x400, v0
	s_waitcnt lgkmcnt(0)
	v_lshl_add_u64 v[16:17], s[0:1], 0, v[2:3]
	v_or_b32_e32 v2, 0x800, v0
	v_lshl_add_u64 v[18:19], s[0:1], 0, v[2:3]
	v_or_b32_e32 v2, 0xc00, v0
	v_lshl_add_u64 v[14:15], s[0:1], 0, v[0:1]
	v_lshl_add_u64 v[20:21], s[0:1], 0, v[2:3]
	v_readlane_b32 s0, v255, 16
	v_readlane_b32 s1, v255, 17
	s_mov_b32 s4, s0
	s_ashr_i32 s5, s0, 31
	s_lshl_b64 s[0:1], s[4:5], 12
	s_add_u32 s0, s2, s0
	s_addc_u32 s1, s3, s1
	v_lshl_add_u64 v[2:3], s[0:1], 0, v[0:1]
	s_mov_b64 s[0:1], 0xc00
	v_lshl_add_u64 v[22:23], v[2:3], 0, s[0:1]
	s_mov_b32 s0, s4
	s_ashr_i32 s47, s46, 31
	v_writelane_b32 v255, s0, 16
	s_lshl_b64 s[2:3], s[46:47], 12
	s_nop 0
	v_writelane_b32 v255, s1, 17
	s_mov_b32 s0, s4
	global_load_dwordx4 v[100:103], v[14:15], off
	global_load_dwordx4 v[104:107], v[16:17], off
	global_load_dwordx4 v[108:111], v[18:19], off
	global_load_dwordx4 v[112:115], v[20:21], off
.LBB0_26:
	global_load_dwordx4 v[24:27], v[22:23], off offset:-3072
	global_load_dwordx4 v[2:5], v[22:23], off offset:-2048
	global_load_dwordx4 v[10:13], v[22:23], off offset:-1024
	global_load_dwordx4 v[6:9], v[22:23], off
	s_add_i32 s0, s0, s46
	s_cmpk_lt_i32 s0, 0x4080
	s_waitcnt vmcnt(2)
	v_mov_b32_e32 v122, v25
	v_mov_b32_e32 v123, v3
	v_mov_b32_e32 v120, v24
	v_mov_b32_e32 v121, v2
	v_pk_mul_f32 v[122:123], v[122:123], v[122:123]
	s_nop 0
	v_pk_fma_f32 v[120:121], v[120:121], v[120:121], v[122:123]
	v_mov_b32_e32 v122, v26
	v_mov_b32_e32 v123, v4
	v_pk_fma_f32 v[120:121], v[122:123], v[122:123], v[120:121]
	v_mov_b32_e32 v122, v27
	v_mov_b32_e32 v123, v5
	v_pk_fma_f32 v[30:31], v[122:123], v[122:123], v[120:121]
	v_add_f32_e32 v0, v30, v31
	s_waitcnt vmcnt(0)
	v_mov_b32_e32 v34, v11
	v_mov_b32_e32 v35, v7
	v_mov_b32_e32 v32, v10
	v_mov_b32_e32 v33, v6
	v_pk_mul_f32 v[34:35], v[34:35], v[34:35]
	s_nop 0
	v_pk_fma_f32 v[32:33], v[32:33], v[32:33], v[34:35]
	v_mov_b32_e32 v34, v12
	v_mov_b32_e32 v35, v8
	v_pk_fma_f32 v[32:33], v[34:35], v[34:35], v[32:33]
	v_mov_b32_e32 v34, v13
	v_mov_b32_e32 v35, v9
	v_pk_fma_f32 v[32:33], v[34:35], v[34:35], v[32:33]
	s_nop 0
	v_add_f32_e32 v0, v0, v32
	v_add_f32_e32 v0, v0, v33
	s_nop 1
	v_add_f32_dpp v0, v0, v0 quad_perm:[1,0,3,2] row_mask:0xf bank_mask:0xf bound_ctrl:1
	s_nop 1
	v_add_f32_dpp v0, v0, v0 quad_perm:[2,3,0,1] row_mask:0xf bank_mask:0xf bound_ctrl:1
	s_nop 1
	v_add_f32_dpp v0, v0, v0 row_half_mirror row_mask:0xf bank_mask:0xf bound_ctrl:1
	s_nop 1
	v_add_f32_dpp v0, v0, v0 row_mirror row_mask:0xf bank_mask:0xf bound_ctrl:1
	ds_bpermute_b32 v30, v28, v0
	s_waitcnt lgkmcnt(0)
	v_add_f32_e32 v0, v0, v30
	ds_bpermute_b32 v30, v29, v0
	s_waitcnt lgkmcnt(0)
	v_add_f32_e32 v0, v0, v30
	v_fmamk_f32 v0, v0, 0x3a800000, v216
	v_cmp_gt_f32_e32 vcc, s63, v0
	v_mul_f32_e32 v30, 0x4b800000, v0
	s_nop 0
	v_cndmask_b32_e32 v0, v0, v30, vcc
	v_rsq_f32_e32 v0, v0
	s_nop 0
	v_mul_f32_e32 v30, 0x45800000, v0
	v_cndmask_b32_e32 v0, v0, v30, vcc
	v_pk_mul_f32 v[24:25], v[24:25], v[0:1] op_sel_hi:[1,0]
	v_pk_mul_f32 v[26:27], v[26:27], v[0:1] op_sel_hi:[1,0]
	v_pk_mul_f32 v[12:13], v[12:13], v[0:1] op_sel_hi:[1,0]
	v_pk_mul_f32 v[10:11], v[10:11], v[0:1] op_sel_hi:[1,0]
	v_pk_mul_f32 v[8:9], v[8:9], v[0:1] op_sel_hi:[1,0]
	v_pk_mul_f32 v[6:7], v[6:7], v[0:1] op_sel_hi:[1,0]
	v_pk_mul_f32 v[26:27], v[102:103], v[26:27]
	v_pk_mul_f32 v[24:25], v[100:101], v[24:25]
	global_store_dwordx4 v[22:23], v[24:27], off offset:-3072
	v_pk_mul_f32 v[124:125], v[4:5], v[0:1] op_sel_hi:[1,0]
	v_pk_mul_f32 v[126:127], v[2:3], v[0:1] op_sel_hi:[1,0]
	v_pk_mul_f32 v[128:129], v[104:105], v[126:127]
	v_pk_mul_f32 v[130:131], v[106:107], v[124:125]
	global_store_dwordx4 v[22:23], v[128:131], off offset:-2048
	v_pk_mul_f32 v[132:133], v[108:109], v[10:11]
	v_pk_mul_f32 v[134:135], v[110:111], v[12:13]
	global_store_dwordx4 v[22:23], v[132:135], off offset:-1024
	v_pk_mul_f32 v[136:137], v[112:113], v[6:7]
	v_pk_mul_f32 v[138:139], v[114:115], v[8:9]
	global_store_dwordx4 v[22:23], v[136:139], off
	v_lshl_add_u64 v[22:23], v[22:23], 0, s[2:3]
	s_cbranch_scc1 .LBB0_26

.LBB0_106:
	s_and_b32 s7, s0, 0x1ffc0
	s_cmpk_lt_i32 s6, 0x4000
	s_cselect_b32 s7, s7, 0x20000
	v_or_b32_e32 v0, s7, v198
	v_lshlrev_b32_e32 v0, 3, v0
	global_load_dwordx2 v[4:5], v0, s[2:3]
	global_load_ushort v100, v[2:3], off offset:-1920
	global_load_ushort v101, v[2:3], off offset:-1792
	global_load_ushort v102, v[2:3], off offset:-896
	global_load_ushort v103, v[2:3], off offset:-768
	global_load_ushort v104, v[2:3], off offset:-1664
	global_load_ushort v105, v[2:3], off offset:-1536
	global_load_ushort v106, v[2:3], off offset:-640
	global_load_ushort v107, v[2:3], off offset:-512
	global_load_ushort v108, v[2:3], off offset:-1408
	global_load_ushort v109, v[2:3], off offset:-1280
	global_load_ushort v110, v[2:3], off offset:-384
	global_load_ushort v111, v[2:3], off offset:-256
	global_load_ushort v112, v[2:3], off offset:-1152
	global_load_ushort v113, v[2:3], off offset:-1024
	global_load_ushort v114, v[2:3], off offset:-128
	global_load_ushort v115, v[2:3], off
	s_add_i32 s6, s6, s46
	s_add_i32 s0, s0, s1
	s_cmpk_gt_i32 s6, 0x407f
	s_waitcnt vmcnt(0)
	v_lshlrev_b32_e32 v120, 16, v100
	v_lshlrev_b32_e32 v121, 16, v101
	v_mul_f32_e32 v122, v5, v121
	v_mul_f32_e32 v123, v4, v121
	v_fma_f32 v122, v4, v120, -v122
	v_fmac_f32_e32 v123, v5, v120
	v_cvt_pk_bf16_f32 v160, v122, v123
	v_lshlrev_b32_e32 v124, 16, v102
	v_mul_f32_e32 v124, 0x3db504f3, v124
	v_lshlrev_b32_e32 v125, 16, v103
	v_mul_f32_e32 v125, 0x3db504f3, v125
	v_mul_f32_e32 v126, v5, v125
	v_mul_f32_e32 v127, v4, v125
	v_fma_f32 v126, v4, v124, -v126
	v_fmac_f32_e32 v127, v5, v124
	v_cvt_pk_bf16_f32 v161, v126, v127
	v_lshlrev_b32_e32 v128, 16, v104
	v_lshlrev_b32_e32 v129, 16, v105
	v_mul_f32_e32 v130, v5, v129
	v_mul_f32_e32 v131, v4, v129
	v_fma_f32 v130, v4, v128, -v130
	v_fmac_f32_e32 v131, v5, v128
	v_cvt_pk_bf16_f32 v162, v130, v131
	v_lshlrev_b32_e32 v132, 16, v106
	v_mul_f32_e32 v132, 0x3db504f3, v132
	v_lshlrev_b32_e32 v133, 16, v107
	v_mul_f32_e32 v133, 0x3db504f3, v133
	v_mul_f32_e32 v134, v5, v133
	v_mul_f32_e32 v135, v4, v133
	v_fma_f32 v134, v4, v132, -v134
	v_fmac_f32_e32 v135, v5, v132
	v_cvt_pk_bf16_f32 v163, v134, v135
	v_lshlrev_b32_e32 v136, 16, v108
	v_lshlrev_b32_e32 v137, 16, v109
	v_mul_f32_e32 v138, v5, v137
	v_mul_f32_e32 v139, v4, v137
	v_fma_f32 v138, v4, v136, -v138
	v_fmac_f32_e32 v139, v5, v136
	v_cvt_pk_bf16_f32 v164, v138, v139
	v_lshlrev_b32_e32 v140, 16, v110
	v_mul_f32_e32 v140, 0x3db504f3, v140
	v_lshlrev_b32_e32 v141, 16, v111
	v_mul_f32_e32 v141, 0x3db504f3, v141
	v_mul_f32_e32 v142, v5, v141
	v_mul_f32_e32 v143, v4, v141
	v_fma_f32 v142, v4, v140, -v142
	v_fmac_f32_e32 v143, v5, v140
	v_cvt_pk_bf16_f32 v165, v142, v143
	v_lshlrev_b32_e32 v144, 16, v112
	v_lshlrev_b32_e32 v145, 16, v113
	v_mul_f32_e32 v146, v5, v145
	v_mul_f32_e32 v147, v4, v145
	v_fma_f32 v146, v4, v144, -v146
	v_fmac_f32_e32 v147, v5, v144
	v_cvt_pk_bf16_f32 v166, v146, v147
	v_lshlrev_b32_e32 v148, 16, v114
	v_mul_f32_e32 v148, 0x3db504f3, v148
	v_lshlrev_b32_e32 v149, 16, v115
	v_mul_f32_e32 v149, 0x3db504f3, v149
	v_mul_f32_e32 v150, v5, v149
	v_mul_f32_e32 v151, v4, v149
	v_fma_f32 v150, v4, v148, -v150
	v_fmac_f32_e32 v151, v5, v148
	v_cvt_pk_bf16_f32 v167, v150, v151
	global_store_short v[2:3], v160, off offset:-1920
	global_store_short_d16_hi v[2:3], v160, off offset:-1792
	global_store_short v[2:3], v161, off offset:-896
	global_store_short_d16_hi v[2:3], v161, off offset:-768
	global_store_short v[2:3], v162, off offset:-1664
	global_store_short_d16_hi v[2:3], v162, off offset:-1536
	global_store_short v[2:3], v163, off offset:-640
	global_store_short_d16_hi v[2:3], v163, off offset:-512
	global_store_short v[2:3], v164, off offset:-1408
	global_store_short_d16_hi v[2:3], v164, off offset:-1280
	global_store_short v[2:3], v165, off offset:-384
	global_store_short_d16_hi v[2:3], v165, off offset:-256
	global_store_short v[2:3], v166, off offset:-1152
	global_store_short_d16_hi v[2:3], v166, off offset:-1024
	global_store_short v[2:3], v167, off offset:-128
	global_store_short_d16_hi v[2:3], v167, off
	v_lshl_add_u64 v[2:3], v[2:3], 0, s[4:5]
	s_cbranch_scc0 .LBB0_106

.LBB0_112:
	v_lshl_add_u64 v[2:3], s[8:9], 0, v[28:29]
	global_load_dwordx4 v[14:17], v[2:3], off
	global_load_dwordx4 v[10:13], v[2:3], off offset:1024
	global_load_dwordx4 v[6:9], v[2:3], off offset:2048
	global_load_dwordx4 v[2:5], v[2:3], off offset:3072
	s_ashr_i32 s6, s12, 11
	s_add_i32 s7, s12, 0xffffc008
	s_cmpk_lt_i32 s12, 0x4000
	s_cselect_b32 s6, s6, s7
	s_mul_hi_i32 s7, s6, 0x6000
	s_mulk_i32 s6, 0x6000
	s_add_u32 s6, s0, s6
	s_addc_u32 s7, s1, s7
	s_add_u32 s10, s6, 0x1000
	s_addc_u32 s11, s7, 0
	global_load_dwordx4 v[100:103], v[18:19], off
	global_load_dwordx4 v[104:107], v32, s[6:7]
	global_load_dwordx4 v[108:111], v32, s[10:11]
	global_load_dwordx4 v[112:115], v[20:21], off
	global_load_dwordx4 v[116:119], v32, s[6:7] offset:1024
	global_load_dwordx4 v[120:123], v33, s[10:11]
	global_load_dwordx4 v[124:127], v[22:23], off
	global_load_dwordx4 v[128:131], v32, s[6:7] offset:2048
	global_load_dwordx4 v[132:135], v34, s[10:11]
	global_load_dwordx4 v[136:139], v[24:25], off
	global_load_dwordx4 v[140:143], v32, s[6:7] offset:3072
	global_load_dwordx4 v[144:147], v35, s[10:11]
	s_mov_b32 s13, 0x1130d000
	s_add_i32 s12, s12, s46
	v_lshl_add_u64 v[28:29], v[28:29], 0, s[4:5]
	s_cmpk_gt_i32 s12, 0x407f
	s_waitcnt vmcnt(14)
	v_mov_b32_e32 v152, v15
	v_mov_b32_e32 v153, v11
	v_mov_b32_e32 v150, v14
	v_mov_b32_e32 v151, v10
	v_pk_mul_f32 v[152:153], v[152:153], v[152:153]
	s_nop 0
	v_pk_fma_f32 v[150:151], v[150:151], v[150:151], v[152:153]
	v_mov_b32_e32 v152, v16
	v_mov_b32_e32 v153, v12
	v_pk_fma_f32 v[150:151], v[152:153], v[152:153], v[150:151]
	v_mov_b32_e32 v152, v17
	v_mov_b32_e32 v153, v13
	v_pk_fma_f32 v[36:37], v[152:153], v[152:153], v[150:151]
	v_add_f32_e32 v0, v36, v37
	s_waitcnt vmcnt(12)
	v_mov_b32_e32 v40, v7
	v_mov_b32_e32 v41, v3
	v_mov_b32_e32 v38, v6
	v_mov_b32_e32 v39, v2
	v_pk_mul_f32 v[40:41], v[40:41], v[40:41]
	s_nop 0
	v_pk_fma_f32 v[38:39], v[38:39], v[38:39], v[40:41]
	v_mov_b32_e32 v40, v8
	v_mov_b32_e32 v41, v4
	v_pk_fma_f32 v[38:39], v[40:41], v[40:41], v[38:39]
	v_mov_b32_e32 v40, v9
	v_mov_b32_e32 v41, v5
	v_pk_fma_f32 v[38:39], v[40:41], v[40:41], v[38:39]
	s_nop 0
	v_add_f32_e32 v0, v0, v38
	v_add_f32_e32 v0, v0, v39
	s_nop 1
	v_add_f32_dpp v0, v0, v0 quad_perm:[1,0,3,2] row_mask:0xf bank_mask:0xf bound_ctrl:1
	s_nop 1
	v_add_f32_dpp v0, v0, v0 quad_perm:[2,3,0,1] row_mask:0xf bank_mask:0xf bound_ctrl:1
	s_nop 1
	v_add_f32_dpp v0, v0, v0 row_half_mirror row_mask:0xf bank_mask:0xf bound_ctrl:1
	s_nop 1
	v_add_f32_dpp v0, v0, v0 row_mirror row_mask:0xf bank_mask:0xf bound_ctrl:1
	ds_bpermute_b32 v36, v30, v0
	s_waitcnt lgkmcnt(0)
	v_add_f32_e32 v0, v0, v36
	ds_bpermute_b32 v36, v31, v0
	s_waitcnt lgkmcnt(0)
	v_add_f32_e32 v0, v0, v36
	v_fmamk_f32 v0, v0, 0x3a800000, v216
	v_cmp_gt_f32_e32 vcc, s63, v0
	v_mul_f32_e32 v36, 0x4b800000, v0
	s_nop 0
	v_cndmask_b32_e32 v0, v0, v36, vcc
	v_rsq_f32_e32 v0, v0
	s_nop 0
	v_mul_f32_e32 v36, 0x45800000, v0
	v_cndmask_b32_e32 v0, v0, v36, vcc
	v_pk_mul_f32 v[16:17], v[16:17], v[0:1] op_sel_hi:[1,0]
	v_pk_mul_f32 v[14:15], v[14:15], v[0:1] op_sel_hi:[1,0]
	v_pk_mul_f32 v[10:11], v[10:11], v[0:1] op_sel_hi:[1,0]
	v_pk_mul_f32 v[12:13], v[12:13], v[0:1] op_sel_hi:[1,0]
	v_pk_mul_f32 v[8:9], v[8:9], v[0:1] op_sel_hi:[1,0]
	v_pk_mul_f32 v[6:7], v[6:7], v[0:1] op_sel_hi:[1,0]
	v_pk_mul_f32 v[4:5], v[4:5], v[0:1] op_sel_hi:[1,0]
	v_pk_mul_f32 v[2:3], v[2:3], v[0:1] op_sel_hi:[1,0]
	s_waitcnt vmcnt(9)
	v_pk_mul_f32 v[14:15], v[100:101], v[14:15]
	v_pk_mul_f32 v[16:17], v[102:103], v[16:17]
	v_pk_add_f32 v[36:37], v[110:111], 1.0 op_sel_hi:[1,0]
	v_pk_add_f32 v[38:39], v[108:109], 1.0 op_sel_hi:[1,0]
	v_pk_fma_f32 v[16:17], v[36:37], v[16:17], v[106:107]
	v_pk_fma_f32 v[14:15], v[38:39], v[14:15], v[104:105]
	s_nop 0
	v_cvt_pk_bf16_f32 v14, v14, v15
	v_cvt_pk_bf16_f32 v15, v16, v17
	v_lshl_add_u64 v[16:17], s[8:9], 0, v[26:27]
	v_add_co_u32_e32 v16, vcc, s13, v16
	v_lshl_add_u64 v[26:27], v[26:27], 0, s[2:3]
	s_nop 0
	v_addc_co_u32_e32 v17, vcc, 0, v17, vcc
	global_store_dwordx2 v[16:17], v[14:15], off offset:256
	s_waitcnt vmcnt(7)
	v_pk_mul_f32 v[10:11], v[112:113], v[10:11]
	v_pk_mul_f32 v[12:13], v[114:115], v[12:13]
	v_pk_add_f32 v[36:37], v[120:121], 1.0 op_sel_hi:[1,0]
	v_pk_add_f32 v[38:39], v[122:123], 1.0 op_sel_hi:[1,0]
	v_pk_fma_f32 v[10:11], v[36:37], v[10:11], v[116:117]
	v_pk_fma_f32 v[12:13], v[38:39], v[12:13], v[118:119]
	v_cvt_pk_bf16_f32 v10, v10, v11
	s_nop 0
	v_cvt_pk_bf16_f32 v11, v12, v13
	global_store_dwordx2 v[16:17], v[10:11], off offset:768
	s_waitcnt vmcnt(5)
	v_pk_mul_f32 v[6:7], v[124:125], v[6:7]
	v_pk_mul_f32 v[8:9], v[126:127], v[8:9]
	v_pk_add_f32 v[36:37], v[132:133], 1.0 op_sel_hi:[1,0]
	v_pk_add_f32 v[38:39], v[134:135], 1.0 op_sel_hi:[1,0]
	v_pk_fma_f32 v[6:7], v[36:37], v[6:7], v[128:129]
	v_pk_fma_f32 v[8:9], v[38:39], v[8:9], v[130:131]
	v_cvt_pk_bf16_f32 v6, v6, v7
	s_nop 0
	v_cvt_pk_bf16_f32 v7, v8, v9
	global_store_dwordx2 v[16:17], v[6:7], off offset:1280
	s_waitcnt vmcnt(3)
	v_pk_mul_f32 v[2:3], v[2:3], v[136:137]
	v_pk_mul_f32 v[4:5], v[4:5], v[138:139]
	v_pk_add_f32 v[36:37], v[144:145], 1.0 op_sel_hi:[1,0]
	v_pk_add_f32 v[38:39], v[146:147], 1.0 op_sel_hi:[1,0]
	v_pk_fma_f32 v[2:3], v[2:3], v[36:37], v[140:141]
	v_pk_fma_f32 v[4:5], v[4:5], v[38:39], v[142:143]
	v_cvt_pk_bf16_f32 v2, v2, v3
	s_nop 0
	v_cvt_pk_bf16_f32 v3, v4, v5
	global_store_dwordx2 v[16:17], v[2:3], off offset:1792
	s_cbranch_scc0 .LBB0_112

.Lml2_nsl0:
	s_add_u32 s22, s22, 0x400
	s_addc_u32 s23, s23, 0
	s_add_u32 s8, s8, 0xc000
	s_addc_u32 s9, s9, 0
	s_add_u32 s10, s10, 0x20000
	s_addc_u32 s11, s11, 0
	s_add_u32 s12, s12, 0x400
	s_addc_u32 s13, s13, 0
	s_waitcnt vmcnt(0)
	v_lshlrev_b32_e32 v88, 16, v80
	v_lshlrev_b32_e32 v89, 16, v81
	v_and_b32_e32 v90, s17, v80
	v_and_b32_e32 v91, s17, v81
	v_lshlrev_b32_e32 v92, 16, v82
	v_and_b32_e32 v93, s17, v82
	v_lshlrev_b32_e32 v94, 16, v83
	v_and_b32_e32 v95, s17, v83
	v_lshlrev_b32_e32 v96, 16, v84
	v_and_b32_e32 v97, s17, v84
	ds_write_b128 v64, v[88:91]
	ds_write_b64 v65, v[92:93]
	ds_write_b64 v66, v[94:95]
	ds_write_b64 v66, v[96:97] offset:128
	ds_write_b32 v67, v85
	s_cmp_lg_u32 s36, 4
	s_cbranch_scc1 .Lml2_nsc0
	v_mov_b32_e32 v98, v87
	s_nop 1
	v_add_f32_dpp v98, v98, v98 row_shr:1 row_mask:0xf bank_mask:0xf bound_ctrl:1
	s_nop 1
	v_add_f32_dpp v98, v98, v98 row_shr:2 row_mask:0xf bank_mask:0xf bound_ctrl:1
	s_nop 1
	v_add_f32_dpp v98, v98, v98 row_shr:4 row_mask:0xf bank_mask:0xf bound_ctrl:1
	s_nop 1
	v_sub_f32_e32 v99, v86, v98
	s_nop 1
	v_max_f32_dpp v99, v99, v99 row_shr:1 row_mask:0xf bank_mask:0xf
	s_nop 1
	v_max_f32_dpp v99, v99, v99 row_shr:2 row_mask:0xf bank_mask:0xf
	s_nop 1
	v_max_f32_dpp v99, v99, v99 row_shr:4 row_mask:0xf bank_mask:0xf
	s_nop 1
	v_max_f32_e32 v99, v99, v0
	v_add_f32_e32 v103, v98, v99
	v_mov_b32_e32 v105, v0
	s_nop 1
	v_mov_b32_dpp v105, v103 row_shr:1 row_mask:0xf bank_mask:0xf
	v_sub_f32_e32 v104, v86, v103
	v_add_f32_e32 v105, v87, v105
	v_fma_f32 v104, v104, s29, v29
	v_sub_f32_e32 v105, v105, v103
	v_exp_f32_e32 v101, v104
	v_mul_f32_e32 v105, s29, v105
	v_mul_f32_e32 v104, 0xbfb8aa3b, v103
	v_exp_f32_e32 v100, v105
	v_exp_f32_e32 v102, v104
	v_readlane_b32 s4, v103, 7
	s_nop 3
	v_mov_b32_e32 v0, s4
	ds_write_b128 v68, v[100:103]

.Lml2_back7:
	v_cvt_pk_bf16_f32 v28, v26, v27
	global_store_dword v4, v28, s[14:15] offset:-4096
	s_waitcnt vmcnt(8)
	v_lshlrev_b32_e32 v88, 16, v80
	v_lshlrev_b32_e32 v89, 16, v81
	v_and_b32_e32 v90, s17, v80
	v_and_b32_e32 v91, s17, v81
	v_lshlrev_b32_e32 v92, 16, v82
	v_and_b32_e32 v93, s17, v82
	v_lshlrev_b32_e32 v94, 16, v83
	v_and_b32_e32 v95, s17, v83
	v_lshlrev_b32_e32 v96, 16, v84
	v_and_b32_e32 v97, s17, v84
	ds_write_b128 v64, v[88:91]
	ds_write_b64 v65, v[92:93]
	ds_write_b64 v66, v[94:95]
	ds_write_b64 v66, v[96:97] offset:128
	ds_write_b32 v67, v85
	s_cmp_lg_u32 s36, 4
	s_cbranch_scc1 .Lml2_nsc2
	v_mov_b32_e32 v98, v87
	s_nop 1
	v_add_f32_dpp v98, v98, v98 row_shr:1 row_mask:0xf bank_mask:0xf bound_ctrl:1
	s_nop 1
	v_add_f32_dpp v98, v98, v98 row_shr:2 row_mask:0xf bank_mask:0xf bound_ctrl:1
	s_nop 1
	v_add_f32_dpp v98, v98, v98 row_shr:4 row_mask:0xf bank_mask:0xf bound_ctrl:1
	s_nop 1
	v_sub_f32_e32 v99, v86, v98
	s_nop 1
	v_max_f32_dpp v99, v99, v99 row_shr:1 row_mask:0xf bank_mask:0xf
	s_nop 1
	v_max_f32_dpp v99, v99, v99 row_shr:2 row_mask:0xf bank_mask:0xf
	s_nop 1
	v_max_f32_dpp v99, v99, v99 row_shr:4 row_mask:0xf bank_mask:0xf
	s_nop 1
	v_max_f32_e32 v99, v99, v0
	v_add_f32_e32 v103, v98, v99
	v_mov_b32_e32 v105, v0
	s_nop 1
	v_mov_b32_dpp v105, v103 row_shr:1 row_mask:0xf bank_mask:0xf
	v_sub_f32_e32 v104, v86, v103
	v_add_f32_e32 v105, v87, v105
	v_fma_f32 v104, v104, s29, v29
	v_sub_f32_e32 v105, v105, v103
	v_exp_f32_e32 v101, v104
	v_mul_f32_e32 v105, s29, v105
	v_mul_f32_e32 v104, 0xbfb8aa3b, v103
	v_exp_f32_e32 v100, v105
	v_exp_f32_e32 v102, v104
	v_readlane_b32 s4, v103, 7
	s_nop 3
	v_mov_b32_e32 v0, s4
	ds_write_b128 v68, v[100:103]

.LBB0_379:
	global_load_dwordx4 v[14:17], v0, s[8:9]
	global_load_dwordx4 v[6:9], v0, s[8:9] offset:1024
	global_load_dwordx4 v[10:13], v0, s[8:9] offset:2048
	global_load_dwordx4 v[2:5], v0, s[8:9] offset:3072
	s_ashr_i32 s8, s6, 11
	s_add_i32 s9, s6, 0xffffc008
	s_and_b64 s[0:1], s[0:1], exec
	s_cselect_b32 s0, s8, s9
	s_mul_hi_i32 s1, s0, 0x6000
	s_mulk_i32 s0, 0x6000
	s_add_u32 s8, s14, s0
	s_addc_u32 s9, s15, s1
	s_add_u32 s10, s8, 0x1000
	s_addc_u32 s11, s9, 0
	global_load_dwordx4 v[28:31], v24, s[10:11]
	global_load_dwordx4 v[32:35], v[18:19], off
	global_load_dwordx4 v[36:39], v24, s[8:9]
	global_load_dwordx4 v[100:103], v[18:19], off offset:1024
	global_load_dwordx4 v[104:107], v25, s[10:11]
	global_load_dwordx4 v[108:111], v24, s[8:9] offset:1024
	global_load_dwordx4 v[112:115], v[18:19], off offset:2048
	global_load_dwordx4 v[116:119], v26, s[10:11]
	global_load_dwordx4 v[120:123], v24, s[8:9] offset:2048
	global_load_dwordx4 v[124:127], v[18:19], off offset:3072
	global_load_dwordx4 v[128:131], v27, s[10:11]
	global_load_dwordx4 v[132:135], v24, s[8:9] offset:3072
	s_lshl_b64 s[0:1], s[12:13], 11
	s_add_u32 s6, s6, s46
	s_addc_u32 s7, s7, s47
	s_add_u32 s2, s2, s4
	s_addc_u32 s3, s3, s5
	s_cmpk_gt_i32 s6, 0x407f
	s_waitcnt vmcnt(15)
	v_mov_b32_e32 v42, v15
	s_waitcnt vmcnt(14)
	v_mov_b32_e32 v43, v7
	v_mov_b32_e32 v40, v14
	v_mov_b32_e32 v41, v6
	s_waitcnt vmcnt(13)
	v_mov_b32_e32 v50, v11
	s_waitcnt vmcnt(12)
	v_mov_b32_e32 v51, v3
	v_pk_mul_f32 v[42:43], v[42:43], v[42:43]
	v_mov_b32_e32 v44, v16
	v_mov_b32_e32 v45, v8
	v_mov_b32_e32 v48, v10
	v_mov_b32_e32 v49, v2
	v_pk_mul_f32 v[50:51], v[50:51], v[50:51]
	v_pk_fma_f32 v[40:41], v[40:41], v[40:41], v[42:43]
	v_mov_b32_e32 v46, v17
	v_mov_b32_e32 v47, v9
	v_mov_b32_e32 v52, v12
	v_mov_b32_e32 v53, v4
	v_pk_fma_f32 v[42:43], v[48:49], v[48:49], v[50:51]
	v_pk_fma_f32 v[40:41], v[44:45], v[44:45], v[40:41]
	v_mov_b32_e32 v54, v13
	v_mov_b32_e32 v55, v5
	v_pk_fma_f32 v[42:43], v[52:53], v[52:53], v[42:43]
	v_pk_fma_f32 v[40:41], v[46:47], v[46:47], v[40:41]
	v_pk_fma_f32 v[42:43], v[54:55], v[54:55], v[42:43]
	v_add_f32_e32 v40, v40, v41
	v_add_f32_e32 v40, v40, v42
	v_add_f32_e32 v40, v40, v43
	s_waitcnt vmcnt(11)
	v_pk_add_f32 v[28:29], v[28:29], 1.0 op_sel_hi:[1,0]
	v_pk_add_f32 v[30:31], v[30:31], 1.0 op_sel_hi:[1,0]
	v_add_f32_dpp v40, v40, v40 quad_perm:[1,0,3,2] row_mask:0xf bank_mask:0xf bound_ctrl:1
	s_nop 1
	v_add_f32_dpp v40, v40, v40 quad_perm:[2,3,0,1] row_mask:0xf bank_mask:0xf bound_ctrl:1
	s_nop 1
	v_add_f32_dpp v40, v40, v40 row_half_mirror row_mask:0xf bank_mask:0xf bound_ctrl:1
	s_nop 1
	v_add_f32_dpp v40, v40, v40 row_mirror row_mask:0xf bank_mask:0xf bound_ctrl:1
	ds_bpermute_b32 v41, v22, v40
	s_waitcnt lgkmcnt(0)
	v_add_f32_e32 v40, v40, v41
	ds_bpermute_b32 v41, v23, v40
	s_waitcnt lgkmcnt(0)
	v_add_f32_e32 v40, v40, v41
	v_fmamk_f32 v40, v40, 0x3a800000, v216
	v_mul_f32_e32 v41, 0x4b800000, v40
	v_cmp_gt_f32_e32 vcc, s63, v40
	s_nop 1
	v_cndmask_b32_e32 v40, v40, v41, vcc
	v_rsq_f32_e32 v42, v40
	v_lshl_add_u64 v[40:41], v[20:21], 0, s[0:1]
	v_mul_f32_e32 v43, 0x45800000, v42
	v_cndmask_b32_e32 v42, v42, v43, vcc
	v_pk_mul_f32 v[14:15], v[14:15], v[42:43] op_sel_hi:[1,0]
	v_pk_mul_f32 v[16:17], v[16:17], v[42:43] op_sel_hi:[1,0]
	s_waitcnt vmcnt(10)
	v_pk_mul_f32 v[14:15], v[32:33], v[14:15]
	v_pk_mul_f32 v[16:17], v[34:35], v[16:17]
	s_waitcnt vmcnt(9)
	v_pk_fma_f32 v[14:15], v[28:29], v[14:15], v[36:37]
	v_pk_fma_f32 v[16:17], v[30:31], v[16:17], v[38:39]
	v_cvt_pk_bf16_f32 v14, v14, v15
	v_pk_mul_f32 v[8:9], v[8:9], v[42:43] op_sel_hi:[1,0]
	v_cvt_pk_bf16_f32 v15, v16, v17
	global_store_dwordx2 v[40:41], v[14:15], off
	v_pk_mul_f32 v[6:7], v[6:7], v[42:43] op_sel_hi:[1,0]
	v_pk_mul_f32 v[12:13], v[12:13], v[42:43] op_sel_hi:[1,0]
	v_pk_mul_f32 v[10:11], v[10:11], v[42:43] op_sel_hi:[1,0]
	v_pk_mul_f32 v[4:5], v[4:5], v[42:43] op_sel_hi:[1,0]
	v_pk_mul_f32 v[2:3], v[2:3], v[42:43] op_sel_hi:[1,0]
	s_waitcnt vmcnt(7)
	v_pk_mul_f32 v[6:7], v[100:101], v[6:7]
	v_pk_mul_f32 v[8:9], v[102:103], v[8:9]
	v_pk_add_f32 v[16:17], v[104:105], 1.0 op_sel_hi:[1,0]
	v_pk_add_f32 v[14:15], v[106:107], 1.0 op_sel_hi:[1,0]
	v_pk_fma_f32 v[6:7], v[16:17], v[6:7], v[108:109]
	v_pk_fma_f32 v[8:9], v[14:15], v[8:9], v[110:111]
	v_cvt_pk_bf16_f32 v6, v6, v7
	s_nop 0
	v_cvt_pk_bf16_f32 v7, v8, v9
	global_store_dwordx2 v[40:41], v[6:7], off offset:512
	s_waitcnt vmcnt(5)
	v_pk_mul_f32 v[6:7], v[112:113], v[10:11]
	v_pk_mul_f32 v[8:9], v[114:115], v[12:13]
	v_pk_add_f32 v[12:13], v[116:117], 1.0 op_sel_hi:[1,0]
	v_pk_add_f32 v[10:11], v[118:119], 1.0 op_sel_hi:[1,0]
	v_pk_fma_f32 v[6:7], v[12:13], v[6:7], v[120:121]
	v_pk_fma_f32 v[8:9], v[10:11], v[8:9], v[122:123]
	v_cvt_pk_bf16_f32 v6, v6, v7
	s_nop 0
	v_cvt_pk_bf16_f32 v7, v8, v9
	global_store_dwordx2 v[40:41], v[6:7], off offset:1024
	s_waitcnt vmcnt(3)
	v_pk_mul_f32 v[2:3], v[2:3], v[124:125]
	v_pk_mul_f32 v[4:5], v[4:5], v[126:127]
	v_pk_add_f32 v[8:9], v[128:129], 1.0 op_sel_hi:[1,0]
	v_pk_add_f32 v[6:7], v[130:131], 1.0 op_sel_hi:[1,0]
	v_pk_fma_f32 v[2:3], v[2:3], v[8:9], v[132:133]
	v_pk_fma_f32 v[4:5], v[4:5], v[6:7], v[134:135]
	v_cvt_pk_bf16_f32 v2, v2, v3
	s_nop 0
	v_cvt_pk_bf16_f32 v3, v4, v5
	global_store_dwordx2 v[40:41], v[2:3], off offset:1536
	s_cbranch_scc1 .LBB0_384
